# combo + bias and mask as the QK accumulator's initial value (16 fewer VALU adds per latent step, bias LDS latency under the K wait) + scan prefetch wait no longer drains the previous chunk's stores
# speedup vs baseline: 1.0090x; 1.0042x over previous
; #define SCAN_BAR() do { asm volatile("s_waitcnt lgkmcnt(0)" ::: "memory"); __builtin_amdgcn_s_barrier(); asm volatile("" ::: "memory"); } while (0)
; __device__ __forceinline__ void scan_phase(const Args& a, LAS unsigned char* lds, int G) {
;     ...
;         SCAN_RAW(0);
;         SCAN_PREP(lds);
;         bf16x8 vf = vfn;
;         SCAN_RAW(1);
;         SCAN_BAR();
.LBB0_86:
	s_or_b64 exec, exec, s[84:85]
	s_and_b64 s[12:13], s[78:79], exec
	s_mov_b32 s12, 0x4800000
	s_cselect_b32 s12, s12, 0x12000000
	s_add_u32 s84, s28, s12
	s_addc_u32 s85, s29, 0
	s_and_b64 s[12:13], s[78:79], exec
	s_cselect_b32 s12, 32, 0xc0
	s_or_b32 s12, s87, s12
	s_or_b32 s13, s12, 31
	v_sub_u32_e32 v0, s13, v98
	v_add_u32_e32 v1, s12, v98
	v_cndmask_b32_e64 v0, v0, v1, s[78:79]
	v_sub_u32_e32 v4, s13, v108
	v_add_u32_e32 v5, s12, v108
	v_sub_u32_e32 v8, s13, v109
	v_add_u32_e32 v9, s12, v109
	v_sub_u32_e32 v12, s13, v110
	v_add_u32_e32 v13, s12, v110
	v_ashrrev_i32_e32 v1, 31, v0
	v_cndmask_b32_e64 v4, v4, v5, s[78:79]
	v_cndmask_b32_e64 v8, v8, v9, s[78:79]
	v_cndmask_b32_e64 v12, v12, v13, s[78:79]
	v_lshlrev_b64 v[0:1], 12, v[0:1]
	v_ashrrev_i32_e32 v5, 31, v4
	v_ashrrev_i32_e32 v9, 31, v8
	v_ashrrev_i32_e32 v13, 31, v12
	v_or_b32_e32 v0, v0, v133
	v_lshlrev_b64 v[4:5], 12, v[4:5]
	v_lshlrev_b64 v[8:9], 12, v[8:9]
	v_lshlrev_b64 v[12:13], 12, v[12:13]
	v_lshl_add_u64 v[2:3], v[0:1], 2, s[82:83]
	v_lshl_add_u64 v[0:1], v[0:1], 1, s[28:29]
	v_or_b32_e32 v4, v4, v133
	v_or_b32_e32 v8, v8, v133
	v_or_b32_e32 v12, v12, v133
	v_lshl_add_u64 v[6:7], v[4:5], 2, s[82:83]
	v_lshl_add_u64 v[4:5], v[4:5], 1, s[28:29]
	v_lshl_add_u64 v[10:11], v[8:9], 2, s[82:83]
	v_lshl_add_u64 v[8:9], v[8:9], 1, s[28:29]
	v_lshl_add_u64 v[14:15], v[12:13], 2, s[82:83]
	v_lshl_add_u64 v[12:13], v[12:13], 1, s[28:29]
	global_load_dword v134, v[2:3], off
	global_load_ushort v135, v[0:1], off
	global_load_dword v136, v[6:7], off
	global_load_ushort v137, v[4:5], off
	global_load_dword v138, v[10:11], off
	global_load_ushort v139, v[8:9], off
	global_load_dword v140, v[14:15], off
	global_load_ushort v141, v[12:13], off
	v_sub_u32_e32 v0, s13, v111
	v_add_u32_e32 v1, s12, v111
	v_cndmask_b32_e64 v0, v0, v1, s[78:79]
	v_sub_u32_e32 v4, s13, v112
	v_add_u32_e32 v5, s12, v112
	v_sub_u32_e32 v8, s13, v113
	v_add_u32_e32 v9, s12, v113
	v_sub_u32_e32 v12, s13, v114
	v_add_u32_e32 v13, s12, v114
	v_ashrrev_i32_e32 v1, 31, v0
	v_cndmask_b32_e64 v4, v4, v5, s[78:79]
	v_cndmask_b32_e64 v8, v8, v9, s[78:79]
	v_cndmask_b32_e64 v12, v12, v13, s[78:79]
	v_lshlrev_b64 v[0:1], 12, v[0:1]
	v_ashrrev_i32_e32 v5, 31, v4
	v_ashrrev_i32_e32 v9, 31, v8
	v_ashrrev_i32_e32 v13, 31, v12
	v_or_b32_e32 v0, v0, v133
	v_lshlrev_b64 v[4:5], 12, v[4:5]
	v_lshlrev_b64 v[8:9], 12, v[8:9]
	v_lshlrev_b64 v[12:13], 12, v[12:13]
	v_lshl_add_u64 v[2:3], v[0:1], 2, s[82:83]
	v_or_b32_e32 v4, v4, v133
	v_or_b32_e32 v8, v8, v133
	v_or_b32_e32 v12, v12, v133
	v_lshl_add_u64 v[0:1], v[0:1], 1, s[28:29]
	v_lshl_add_u64 v[6:7], v[4:5], 2, s[82:83]
	v_lshl_add_u64 v[4:5], v[4:5], 1, s[28:29]
	v_lshl_add_u64 v[10:11], v[8:9], 2, s[82:83]
	v_lshl_add_u64 v[8:9], v[8:9], 1, s[28:29]
	v_lshl_add_u64 v[14:15], v[12:13], 2, s[82:83]
	v_lshl_add_u64 v[12:13], v[12:13], 1, s[28:29]
	global_load_dword v142, v[2:3], off
	global_load_ushort v143, v[0:1], off
	global_load_dword v144, v[6:7], off
	global_load_ushort v145, v[4:5], off
	global_load_dword v146, v[10:11], off
	global_load_ushort v147, v[8:9], off
	global_load_dword v148, v[14:15], off
	global_load_ushort v149, v[12:13], off
	v_sub_u32_e32 v0, s12, v100
	v_add_u32_e32 v0, 24, v0
	v_or_b32_e32 v1, s12, v100
	v_cndmask_b32_e64 v0, v0, v1, s[78:79]
	v_ashrrev_i32_e32 v1, 31, v0
	v_lshl_add_u64 v[0:1], v[0:1], 1, v[92:93]
	global_load_dwordx4 v[40:43], v[0:1], off
	s_lshl_b32 s88, s15, 11
	s_lshl_b32 s12, s23, 1
	s_add_u32 s12, s84, s12
	s_addc_u32 s13, s85, 0
	s_waitcnt lgkmcnt(0)
	s_barrier
	v_lshl_add_u64 v[0:1], v[86:87], 1, s[12:13]
	v_lshl_add_u64 v[94:95], v[0:1], 0, v[96:97]
	v_mov_b32_e32 v0, 0
	s_movk_i32 s89, 0x47
	s_mov_b32 s90, -8
	v_mov_b32_e32 v1, v0
	v_mov_b32_e32 v2, v0
	v_mov_b32_e32 v3, v0
	v_mov_b32_e32 v24, v0
	v_mov_b32_e32 v25, v0
	v_mov_b32_e32 v26, v0
	v_mov_b32_e32 v27, v0
	v_mov_b32_e32 v12, v0
	v_mov_b32_e32 v13, v0
	v_mov_b32_e32 v14, v0
	v_mov_b32_e32 v15, v0
	v_mov_b32_e32 v20, v0
	v_mov_b32_e32 v21, v0
	v_mov_b32_e32 v22, v0
	v_mov_b32_e32 v23, v0
	v_mov_b32_e32 v8, v0
	v_mov_b32_e32 v9, v0
	v_mov_b32_e32 v10, v0
	v_mov_b32_e32 v11, v0
	v_mov_b32_e32 v16, v0
	v_mov_b32_e32 v17, v0
	v_mov_b32_e32 v18, v0
	v_mov_b32_e32 v19, v0
	v_mov_b32_e32 v4, v0
	v_mov_b32_e32 v5, v0
	v_mov_b32_e32 v6, v0
	v_mov_b32_e32 v7, v0
	v_mov_b32_e32 v28, v0
	v_mov_b32_e32 v29, v0
	v_mov_b32_e32 v30, v0
	v_mov_b32_e32 v31, v0
	s_waitcnt vmcnt(0)
.LBB0_87:
	s_waitcnt vmcnt(16)
	v_add_f32_e32 v45, 0, v134
	s_waitcnt vmcnt(14)
	v_add_f32_e32 v52, v45, v136
	s_waitcnt vmcnt(12)
	v_add_f32_e32 v53, v52, v138
	s_waitcnt vmcnt(10)
	v_add_f32_e32 v54, v53, v140
	s_waitcnt vmcnt(8)
	v_add_f32_e32 v55, v54, v142
	s_waitcnt vmcnt(6)
	v_add_f32_e32 v56, v55, v144
	s_waitcnt vmcnt(4)
	v_add_f32_e32 v57, v56, v146
	s_waitcnt vmcnt(2)
	v_add_f32_e32 v58, v57, v148
	ds_write_b32 v101, v58 offset:56320
	s_waitcnt lgkmcnt(0)
	s_barrier
	ds_read2st64_b32 v[46:47], v102 offset0:220 offset1:222
	ds_read2st64_b32 v[48:49], v102 offset0:224 offset1:226
	s_waitcnt vmcnt(2)
	v_mov_b64_e32 v[32:33], v[40:41]
	v_mov_b64_e32 v[34:35], v[42:43]
	v_mul_f32_e32 v44, 0x3fb8aa3b, v134
	s_waitcnt lgkmcnt(1)
	v_add_f32_e32 v50, 0, v46
	v_cndmask_b32_e64 v40, 0, v47, s[40:41]
	v_cndmask_b32_e64 v42, 0, v50, s[38:39]
	s_waitcnt lgkmcnt(0)
	v_cndmask_b32_e64 v41, 0, v48, s[42:43]
	v_add_f32_e32 v51, v42, v40
	v_mov_b32_e32 v40, v47
	v_cndmask_b32_e64 v43, 0, v49, s[44:45]
	v_pk_add_f32 v[40:41], v[50:51], v[40:41]
	v_mov_b32_e32 v42, v48
	v_exp_f32_e32 v46, v44
	v_pk_add_f32 v[42:43], v[40:41], v[42:43]
	v_mov_b32_e32 v44, v49
	v_pk_add_f32 v[40:41], v[42:43], v[44:45]
	s_bitcmp1_b32 s90, 0
	v_mul_f32_e32 v44, 0x3fb8aa3b, v41
	v_mul_f32_e32 v45, 0xbfb8aa3b, v41
	v_sub_f32_e32 v41, v40, v41
	v_exp_f32_e32 v44, v44
	v_mul_f32_e32 v41, 0x3fb8aa3b, v41
	v_exp_f32_e32 v45, v45
	v_exp_f32_e32 v41, v41
	s_cselect_b32 s12, 0, 0x6e00
	v_sub_f32_e32 v42, 1.0, v46
	v_lshlrev_b32_e32 v46, 16, v135
	s_add_i32 s15, s12, 0
	v_mul_f32_e32 v44, v44, v46
	v_mul_f32_e32 v45, v42, v45
	v_mul_f32_e32 v41, v42, v41
	v_cvt_pk_bf16_f32 v42, v44, s0
	v_lshl_add_u32 v44, v88, 1, s15
	ds_write_b16 v44, v42
	v_cvt_pk_bf16_f32 v42, v45, s0
	ds_write_b16 v44, v42 offset:8704
	v_add_f32_e32 v44, v52, v43
	v_mul_f32_e32 v42, 0x3fb8aa3b, v136
	v_mul_f32_e32 v45, 0x3fb8aa3b, v44
	v_mul_f32_e32 v46, 0xbfb8aa3b, v44
	v_sub_f32_e32 v44, v40, v44
	v_exp_f32_e32 v42, v42
	v_exp_f32_e32 v45, v45
	v_mul_f32_e32 v44, 0x3fb8aa3b, v44
	v_exp_f32_e32 v46, v46
	v_exp_f32_e32 v44, v44
	v_lshlrev_b32_e32 v47, 16, v137
	v_sub_f32_e32 v42, 1.0, v42
	v_mul_f32_e32 v45, v45, v47
	v_mul_f32_e32 v46, v42, v46
	v_mul_f32_e32 v42, v42, v44
	v_cvt_pk_bf16_f32 v44, v45, s0
	v_lshl_add_u32 v45, v90, 1, s15
	ds_write_b16 v45, v44
	v_cvt_pk_bf16_f32 v44, v46, s0
	v_mul_f32_e32 v46, 0x3fb8aa3b, v138
	v_exp_f32_e32 v46, v46
	ds_write_b16 v45, v44 offset:8704
	v_add_f32_e32 v44, v53, v43
	v_mul_f32_e32 v47, 0xbfb8aa3b, v44
	v_sub_f32_e32 v45, 1.0, v46
	v_mul_f32_e32 v46, 0x3fb8aa3b, v44
	v_sub_f32_e32 v44, v40, v44
	v_exp_f32_e32 v46, v46
	v_mul_f32_e32 v44, 0x3fb8aa3b, v44
	v_exp_f32_e32 v47, v47
	v_exp_f32_e32 v44, v44
	v_lshlrev_b32_e32 v48, 16, v139
	v_mul_f32_e32 v46, v46, v48
	v_mul_f32_e32 v47, v45, v47
	v_mul_f32_e32 v44, v45, v44
	v_cvt_pk_bf16_f32 v45, v46, s0
	v_lshl_add_u32 v46, v115, 1, s15
	ds_write_b16 v46, v45
	v_cvt_pk_bf16_f32 v45, v47, s0
	ds_write_b16 v46, v45 offset:8704
	v_add_f32_e32 v46, v54, v43
	v_mul_f32_e32 v45, 0x3fb8aa3b, v140
	v_mul_f32_e32 v47, 0x3fb8aa3b, v46
	v_mul_f32_e32 v48, 0xbfb8aa3b, v46
	v_sub_f32_e32 v46, v40, v46
	v_exp_f32_e32 v45, v45
	v_exp_f32_e32 v47, v47
	v_mul_f32_e32 v46, 0x3fb8aa3b, v46
	v_exp_f32_e32 v48, v48
	v_exp_f32_e32 v46, v46
	v_lshlrev_b32_e32 v49, 16, v141
	v_sub_f32_e32 v45, 1.0, v45
	v_mul_f32_e32 v47, v47, v49
	v_mul_f32_e32 v48, v45, v48
	v_mul_f32_e32 v45, v45, v46
	v_cvt_pk_bf16_f32 v46, v47, s0
	v_lshl_add_u32 v47, v117, 1, s15
	ds_write_b16 v47, v46
	v_cvt_pk_bf16_f32 v46, v48, s0
	v_mul_f32_e32 v48, 0x3fb8aa3b, v142
	v_exp_f32_e32 v48, v48
	ds_write_b16 v47, v46 offset:8704
	v_add_f32_e32 v46, v55, v43
	v_mul_f32_e32 v49, 0xbfb8aa3b, v46
	v_sub_f32_e32 v47, 1.0, v48
	v_mul_f32_e32 v48, 0x3fb8aa3b, v46
	v_sub_f32_e32 v46, v40, v46
	v_exp_f32_e32 v48, v48
	v_mul_f32_e32 v46, 0x3fb8aa3b, v46
	v_exp_f32_e32 v49, v49
	v_exp_f32_e32 v46, v46
	v_lshlrev_b32_e32 v50, 16, v143
	v_mul_f32_e32 v48, v48, v50
	v_mul_f32_e32 v49, v47, v49
	v_mul_f32_e32 v46, v47, v46
	v_cvt_pk_bf16_f32 v47, v48, s0
	v_lshl_add_u32 v48, v119, 1, s15
	ds_write_b16 v48, v47
	v_cvt_pk_bf16_f32 v47, v49, s0
	ds_write_b16 v48, v47 offset:8704
	v_add_f32_e32 v48, v56, v43
	v_mul_f32_e32 v47, 0x3fb8aa3b, v144
	v_mul_f32_e32 v49, 0x3fb8aa3b, v48
	v_mul_f32_e32 v50, 0xbfb8aa3b, v48
	v_sub_f32_e32 v48, v40, v48
	v_exp_f32_e32 v47, v47
	v_exp_f32_e32 v49, v49
	v_mul_f32_e32 v48, 0x3fb8aa3b, v48
	v_exp_f32_e32 v50, v50
	v_exp_f32_e32 v48, v48
	v_lshlrev_b32_e32 v51, 16, v145
	v_sub_f32_e32 v47, 1.0, v47
	v_mul_f32_e32 v49, v49, v51
	v_mul_f32_e32 v50, v47, v50
	v_mul_f32_e32 v47, v47, v48
	v_cvt_pk_bf16_f32 v48, v49, s0
	v_lshl_add_u32 v49, v121, 1, s15
	ds_write_b16 v49, v48
	v_cvt_pk_bf16_f32 v48, v50, s0
	v_mul_f32_e32 v50, 0x3fb8aa3b, v146
	v_exp_f32_e32 v50, v50
	ds_write_b16 v49, v48 offset:8704
	v_add_f32_e32 v48, v57, v43
	v_mul_f32_e32 v51, 0xbfb8aa3b, v48
	v_sub_f32_e32 v49, 1.0, v50
	v_mul_f32_e32 v50, 0x3fb8aa3b, v48
	v_sub_f32_e32 v48, v40, v48
	v_exp_f32_e32 v50, v50
	v_mul_f32_e32 v48, 0x3fb8aa3b, v48
	v_exp_f32_e32 v51, v51
	v_exp_f32_e32 v48, v48
	v_lshlrev_b32_e32 v52, 16, v147
	v_mul_f32_e32 v50, v50, v52
	v_mul_f32_e32 v51, v49, v51
	v_mul_f32_e32 v48, v49, v48
	v_cvt_pk_bf16_f32 v49, v50, s0
	v_lshl_add_u32 v50, v123, 1, s15
	ds_write_b16 v50, v49
	v_cvt_pk_bf16_f32 v49, v51, s0
	v_add_f32_e32 v43, v58, v43
	ds_write_b16 v50, v49 offset:8704
	v_mul_f32_e32 v49, 0x3fb8aa3b, v148
	v_mul_f32_e32 v50, 0x3fb8aa3b, v43
	v_mul_f32_e32 v51, 0xbfb8aa3b, v43
	v_sub_f32_e32 v43, v40, v43
	v_exp_f32_e32 v49, v49
	v_exp_f32_e32 v50, v50
	v_mul_f32_e32 v43, 0x3fb8aa3b, v43
	v_exp_f32_e32 v51, v51
	v_exp_f32_e32 v43, v43
	v_lshlrev_b32_e32 v52, 16, v149
	v_sub_f32_e32 v49, 1.0, v49
	v_mul_f32_e32 v50, v50, v52
	v_cvt_pk_bf16_f32 v41, v41, s0
	v_mul_f32_e32 v51, v49, v51
	v_mul_f32_e32 v43, v49, v43
	v_cvt_pk_bf16_f32 v49, v50, s0
	v_lshl_add_u32 v50, v125, 1, s15
	v_perm_b32 v41, 0, v41, v216
	v_cvt_pk_bf16_f32 v42, v42, s0
	v_cvt_pk_bf16_f32 v44, v44, s0
	v_cvt_pk_bf16_f32 v46, v46, s0
	v_cvt_pk_bf16_f32 v48, v48, s0
	ds_write_b16 v50, v49
	v_cvt_pk_bf16_f32 v49, v51, s0
	v_perm_b32 v44, 0, v44, v216
	v_cvt_pk_bf16_f32 v45, v45, s0
	v_perm_b32 v46, 0, v46, v216
	v_cvt_pk_bf16_f32 v47, v47, s0
	v_perm_b32 v48, 0, v48, v216
	ds_write_b16 v50, v49 offset:8704
	v_cvt_pk_bf16_f32 v49, v43, s0
	v_lshl_or_b32 v42, v42, 16, v41
	v_add_u32_e32 v41, s15, v103
	v_lshl_or_b32 v43, v45, 16, v44
	v_lshl_or_b32 v44, v47, 16, v46
	v_lshl_or_b32 v45, v49, 16, v48
	v_add_u32_e32 v46, v41, v105
	ds_write_b128 v46, v[42:45] offset:17408
	s_and_saveexec_b64 s[84:85], s[36:37]
	s_cbranch_execz .LBB0_89
	v_mul_f32_e32 v40, 0x3fb8aa3b, v40
	v_exp_f32_e32 v40, v40
	v_add_u32_e32 v41, v41, v106
	ds_write_b32 v41, v40 offset:27648

; __device__ __forceinline__ void attn_phase(const Args& a, int layer, LAS unsigned char* lds, int G, int need_ctx) {
;     ...
;         for (int st = 0; st < nst; ++st) {
;             const bool isl = st < nband;
;             const int keybase = isl ? kb_lat + st * 64 : kb_ctx + 32 * (st - nband);
; #pragma unroll
;             for (int d = 0; d < 4; ++d)
; #pragma unroll
;                 for (int s2 = 0; s2 < 2; ++s2) vreg[d * 2 + s2] = *(const bf16x8*)(vbase + (size_t)(keybase >> 3) * 32768 + s2 * 65536 + d * 256);
;             f32x16 sc;
; #pragma unroll
;             for (int t = 0; t < 16; ++t) sc[t] = 0.f;
; #pragma unroll
;             for (int c = 0; c < 8; ++c) sc = __builtin_amdgcn_mfma_f32_32x32x16_bf16(kreg[c], qf[c], sc, 0, 0, 0);
;             if (st + 1 < nst) {
;                 const int kn = (st + 1 < nband) ? kb_lat + (st + 1) * 64 : kb_ctx + 32 * (st + 1 - nband);
; #pragma unroll
;                 for (int c = 0; c < 8; ++c) kreg[c] = *(const bf16x8*)(kbase + (size_t)(kn >> 3) * 32768 + 128 * c);
;             }
;             if (isl) {
;                 const int kr = r0a + st; const bool rowok = (kr >= myr0) && (kr < myr0 + 8);
;                 const int brow = (kr - qr + 7) * 31 - qcol + 15;
; #pragma unroll
;                 for (int t = 0; t < 16; ++t) {
;                     const int kc = cw + 16 * (t >> 3) + 8 * hh + (t & 7); const bool valid = rowok && (kc >= c0) && (kc < c0 + 16);
;                     const float bias = rp[valid ? (brow + kc) : 0];
;                     sc[t] = valid ? sc[t] + bias : -3.0e38f;
;                 }
;             }
.LBB0_156:
	s_ashr_i32 s12, s12, 3
	s_ashr_i32 s13, s12, 31
	s_lshl_b64 s[12:13], s[12:13], 16
	v_lshl_add_u64 v[64:65], v[208:209], 0, s[12:13]
	v_add_co_u32_e32 v66, vcc, 0x20000, v64
	global_load_dwordx4 v[190:193], v[64:65], off
	s_nop 0
	v_addc_co_u32_e32 v67, vcc, 0, v65, vcc
	global_load_dwordx4 v[186:189], v[66:67], off
	global_load_dwordx4 v[182:185], v[64:65], off offset:512
	global_load_dwordx4 v[178:181], v[66:67], off offset:512
	global_load_dwordx4 v[174:177], v[64:65], off offset:1024
	global_load_dwordx4 v[170:173], v[66:67], off offset:1024
	global_load_dwordx4 v[166:169], v[64:65], off offset:1536
	global_load_dwordx4 v[162:165], v[66:67], off offset:1536
	s_andn2_b64 vcc, exec, s[6:7]
	s_cbranch_vccnz .Latt_qk_ctx
	s_add_i32 s12, s37, s27
	v_cmp_ge_u32_e64 s[6:7], s12, v96
	v_cmp_lt_u32_e32 vcc, s12, v234
	s_and_b64 s[6:7], s[6:7], vcc
	v_cndmask_b32_e64 v253, v232, v236, s[6:7]
	ds_read2_b32 v[80:81], v253 offset0:0 offset1:1
	ds_read2_b32 v[82:83], v253 offset0:2 offset1:3
	ds_read2_b32 v[84:85], v253 offset0:4 offset1:5
	ds_read2_b32 v[86:87], v253 offset0:6 offset1:7
	ds_read2_b32 v[88:89], v253 offset0:16 offset1:17
	ds_read2_b32 v[90:91], v253 offset0:18 offset1:19
	ds_read2_b32 v[92:93], v253 offset0:20 offset1:21
	ds_read2_b32 v[94:95], v253 offset0:22 offset1:23
	s_and_b64 vcc, s[6:7], s[0:1]
	s_waitcnt lgkmcnt(7)
	v_cndmask_b32_e32 v64, v254, v80, vcc
	s_and_b64 s[12:13], s[6:7], s[40:41]
	v_cndmask_b32_e64 v65, v254, v81, s[12:13]
	s_and_b64 vcc, s[6:7], s[44:45]
	s_waitcnt lgkmcnt(6)
	v_cndmask_b32_e32 v66, v254, v82, vcc
	s_and_b64 s[12:13], s[6:7], s[48:49]
	v_cndmask_b32_e64 v67, v254, v83, s[12:13]
	s_and_b64 vcc, s[6:7], s[52:53]
	s_waitcnt lgkmcnt(5)
	v_cndmask_b32_e32 v68, v254, v84, vcc
	s_and_b64 s[12:13], s[6:7], s[56:57]
	v_cndmask_b32_e64 v69, v254, v85, s[12:13]
	s_and_b64 vcc, s[6:7], s[60:61]
	s_waitcnt lgkmcnt(4)
	v_cndmask_b32_e32 v70, v254, v86, vcc
	s_and_b64 s[12:13], s[6:7], s[64:65]
	v_cndmask_b32_e64 v71, v254, v87, s[12:13]
	s_and_b64 vcc, s[6:7], s[68:69]
	s_waitcnt lgkmcnt(3)
	v_cndmask_b32_e32 v72, v254, v88, vcc
	s_and_b64 s[12:13], s[6:7], s[72:73]
	v_cndmask_b32_e64 v73, v254, v89, s[12:13]
	s_and_b64 vcc, s[6:7], s[76:77]
	s_waitcnt lgkmcnt(2)
	v_cndmask_b32_e32 v74, v254, v90, vcc
	s_and_b64 s[12:13], s[6:7], s[82:83]
	v_cndmask_b32_e64 v75, v254, v91, s[12:13]
	s_and_b64 vcc, s[6:7], s[86:87]
	s_waitcnt lgkmcnt(1)
	v_cndmask_b32_e32 v76, v254, v92, vcc
	s_and_b64 s[12:13], s[6:7], s[90:91]
	v_cndmask_b32_e64 v77, v254, v93, s[12:13]
	s_and_b64 vcc, s[6:7], s[94:95]
	s_waitcnt lgkmcnt(0)
	v_cndmask_b32_e32 v78, v254, v94, vcc
	s_and_b64 s[12:13], s[6:7], s[98:99]
	v_cndmask_b32_e64 v79, v254, v95, s[12:13]
	s_waitcnt vmcnt(8)
	s_nop 1
	v_mfma_f32_32x32x16_bf16 v[64:79], v[146:149], v[98:101], v[64:79]
	s_branch .Latt_qk_rest
.Latt_qk_ctx:
	s_waitcnt vmcnt(8)
	v_mfma_f32_32x32x16_bf16 v[64:79], v[146:149], v[98:101], 0
.Latt_qk_rest:
	s_add_i32 s26, s27, 1
	s_cmp_ge_i32 s26, s25
	v_mfma_f32_32x32x16_bf16 v[64:79], v[150:153], v[102:105], v[64:79]
	v_mfma_f32_32x32x16_bf16 v[64:79], v[154:157], v[106:109], v[64:79]
	v_mfma_f32_32x32x16_bf16 v[64:79], v[158:161], v[110:113], v[64:79]
	v_mfma_f32_32x32x16_bf16 v[64:79], v[142:145], v[114:117], v[64:79]
	v_mfma_f32_32x32x16_bf16 v[64:79], v[138:141], v[118:121], v[64:79]
	v_mfma_f32_32x32x16_bf16 v[64:79], v[134:137], v[122:125], v[64:79]
	v_mfma_f32_32x32x16_bf16 v[64:79], v[130:133], v[126:129], v[64:79]
	s_cbranch_scc1 .LBB0_162
	s_sub_i32 s12, s26, s100
	s_cmp_lt_u32 s12, s15
	s_cbranch_scc1 .Latt_lat_nxt
	s_add_i32 s12, s23, 32
	s_cmp_lt_i32 s26, s100
	s_cbranch_scc0 .LBB0_161
	s_lshl_b32 s13, s15, 5
	s_add_i32 s12, s12, s13
	s_branch .LBB0_161

; __device__ __forceinline__ void attn_phase(const Args& a, int layer, LAS unsigned char* lds, int G, int need_ctx) {
;     ...
;             if (isl) {
;                 const int kr = r0a + st; const bool rowok = (kr >= myr0) && (kr < myr0 + 8);
;                 const int brow = (kr - qr + 7) * 31 - qcol + 15;
; #pragma unroll
;                 for (int t = 0; t < 16; ++t) {
;                     const int kc = cw + 16 * (t >> 3) + 8 * hh + (t & 7); const bool valid = rowok && (kc >= c0) && (kc < c0 + 16);
;                     const float bias = rp[valid ? (brow + kc) : 0];
;                     sc[t] = valid ? sc[t] + bias : -3.0e38f;
;                 }
;             }
;             float mx = sc[0];
; #pragma unroll
;             for (int t = 1; t < 16; ++t) mx = fmaxf(mx, sc[t]);
;             mx = fmaxf(mx, __shfl_xor(mx, 32));
;             const float m_new = fmaxf(m_run, mx), alpha = __expf(m_run - m_new);
;             float rs = 0.f;
; #pragma unroll
;             for (int t = 0; t < 16; ++t) { sc[t] = __expf(sc[t] - m_new); rs += sc[t]; }
;             rs += __shfl_xor(rs, 32);
;             l_run = l_run * alpha + rs; m_run = m_new;
;             union { u32x4 u; bf16x8 v; } P0, P1;
;             P0.u.x = pk2(sc[0], sc[1]); P0.u.y = pk2(sc[2], sc[3]); P0.u.z = pk2(sc[4], sc[5]); P0.u.w = pk2(sc[6], sc[7]);
;             P1.u.x = pk2(sc[8], sc[9]); P1.u.y = pk2(sc[10], sc[11]); P1.u.z = pk2(sc[12], sc[13]); P1.u.w = pk2(sc[14], sc[15]);
; #pragma unroll
;             for (int d = 0; d < 4; ++d) {
; #pragma unroll
;                 for (int t = 0; t < 16; ++t) OT[d][t] *= alpha;
.LBB0_162:
.LBB0_196:
	s_nop 8
	v_max3_f32 v80, v64, v65, v66
	v_max3_f32 v81, v67, v68, v69
	v_max3_f32 v82, v70, v71, v72
	v_max3_f32 v83, v73, v74, v75
	v_max3_f32 v84, v76, v77, v78
	v_max3_f32 v80, v80, v81, v82
	v_max3_f32 v83, v83, v84, v79
	v_max_f32_e32 v80, v80, v83
	ds_bpermute_b32 v81, v235, v80
	s_add_i32 s23, s23, 32
	v_add_u32_e32 v236, 0x7c, v236
	s_mov_b32 s12, 0x3fb8aa3b
	s_waitcnt lgkmcnt(0)
	v_max_f32_e32 v80, v80, v81
	v_max_f32_e32 v81, v238, v80
	v_sub_f32_e32 v82, v81, v238
	v_cmp_lt_f32_e32 vcc, 0x40a00000, v82
	s_nop 1
	v_cndmask_b32_e32 v80, v238, v81, vcc
	v_mul_f32_e32 v83, s12, v80
	v_sub_f32_e32 v84, v238, v80
	v_mul_f32_e32 v87, s12, v80
	v_mul_f32_e32 v84, s12, v84
	v_fma_f32 v64, v64, s12, -v87
	v_fma_f32 v65, v65, s12, -v87
	v_exp_f32_e32 v86, v84
	v_exp_f32_e32 v64, v64
	v_fma_f32 v66, v66, s12, -v87
	v_mov_b32_e32 v238, v80
	v_exp_f32_e32 v65, v65
	v_fma_f32 v67, v67, s12, -v87
	v_add_f32_e32 v88, v64, v65
	v_exp_f32_e32 v66, v66
	v_fma_f32 v68, v68, s12, -v87
	v_cvt_pk_bf16_f32 v80, v64, v65
	v_exp_f32_e32 v67, v67
	v_fma_f32 v69, v69, s12, -v87
	v_add_f32_e32 v89, v66, v67
	v_exp_f32_e32 v68, v68
	v_fma_f32 v70, v70, s12, -v87
	v_cvt_pk_bf16_f32 v81, v66, v67
	v_add_f32_e32 v88, v88, v68
	v_exp_f32_e32 v69, v69
	v_fma_f32 v71, v71, s12, -v87
	v_add_f32_e32 v89, v89, v69
	v_exp_f32_e32 v70, v70
	v_fma_f32 v72, v72, s12, -v87
	v_cvt_pk_bf16_f32 v82, v68, v69
	v_add_f32_e32 v88, v88, v70
	v_exp_f32_e32 v71, v71
	v_fma_f32 v73, v73, s12, -v87
	v_add_f32_e32 v89, v89, v71
	v_exp_f32_e32 v72, v72
	v_fma_f32 v74, v74, s12, -v87
	v_cvt_pk_bf16_f32 v83, v70, v71
	v_add_f32_e32 v88, v88, v72
	v_exp_f32_e32 v73, v73
	v_fma_f32 v75, v75, s12, -v87
	v_add_f32_e32 v89, v89, v73
	v_exp_f32_e32 v74, v74
	v_fma_f32 v76, v76, s12, -v87
	v_cvt_pk_bf16_f32 v92, v72, v73
	v_add_f32_e32 v88, v88, v74
	v_exp_f32_e32 v75, v75
	v_fma_f32 v77, v77, s12, -v87
	v_add_f32_e32 v89, v89, v75
	v_exp_f32_e32 v76, v76
	v_fma_f32 v78, v78, s12, -v87
	v_cvt_pk_bf16_f32 v93, v74, v75
	v_add_f32_e32 v88, v88, v76
	v_exp_f32_e32 v77, v77
	v_fma_f32 v79, v79, s12, -v87
	v_add_f32_e32 v89, v89, v77
	v_exp_f32_e32 v78, v78
	v_cvt_pk_bf16_f32 v94, v76, v77
	v_add_f32_e32 v88, v88, v78
	v_exp_f32_e32 v79, v79
	s_nop 0
	v_add_f32_e32 v89, v89, v79
	v_cvt_pk_bf16_f32 v95, v78, v79
	v_add_f32_e32 v88, v88, v89
	v_fma_f32 v237, v237, v86, v88
	s_and_b64 vcc, exec, vcc
	s_cbranch_vccz .Latt_norescale
	v_pk_mul_f32 v[62:63], v[62:63], v[86:87] op_sel_hi:[1,0]
	v_pk_mul_f32 v[60:61], v[60:61], v[86:87] op_sel_hi:[1,0]
	v_pk_mul_f32 v[58:59], v[58:59], v[86:87] op_sel_hi:[1,0]
	v_pk_mul_f32 v[56:57], v[56:57], v[86:87] op_sel_hi:[1,0]
	v_pk_mul_f32 v[54:55], v[54:55], v[86:87] op_sel_hi:[1,0]
	v_pk_mul_f32 v[52:53], v[52:53], v[86:87] op_sel_hi:[1,0]
	v_pk_mul_f32 v[50:51], v[50:51], v[86:87] op_sel_hi:[1,0]
	v_pk_mul_f32 v[48:49], v[48:49], v[86:87] op_sel_hi:[1,0]
	v_pk_mul_f32 v[46:47], v[46:47], v[86:87] op_sel_hi:[1,0]
	v_pk_mul_f32 v[44:45], v[44:45], v[86:87] op_sel_hi:[1,0]
	v_pk_mul_f32 v[42:43], v[42:43], v[86:87] op_sel_hi:[1,0]
	v_pk_mul_f32 v[40:41], v[40:41], v[86:87] op_sel_hi:[1,0]
	v_pk_mul_f32 v[38:39], v[38:39], v[86:87] op_sel_hi:[1,0]
	v_pk_mul_f32 v[36:37], v[36:37], v[86:87] op_sel_hi:[1,0]
	v_pk_mul_f32 v[34:35], v[34:35], v[86:87] op_sel_hi:[1,0]
	v_pk_mul_f32 v[32:33], v[32:33], v[86:87] op_sel_hi:[1,0]
	v_pk_mul_f32 v[30:31], v[30:31], v[86:87] op_sel_hi:[1,0]
	v_pk_mul_f32 v[28:29], v[28:29], v[86:87] op_sel_hi:[1,0]
	v_pk_mul_f32 v[26:27], v[26:27], v[86:87] op_sel_hi:[1,0]
	v_pk_mul_f32 v[24:25], v[24:25], v[86:87] op_sel_hi:[1,0]
	v_pk_mul_f32 v[22:23], v[22:23], v[86:87] op_sel_hi:[1,0]
	v_pk_mul_f32 v[20:21], v[20:21], v[86:87] op_sel_hi:[1,0]
	v_pk_mul_f32 v[18:19], v[18:19], v[86:87] op_sel_hi:[1,0]
	v_pk_mul_f32 v[16:17], v[16:17], v[86:87] op_sel_hi:[1,0]
	v_pk_mul_f32 v[14:15], v[14:15], v[86:87] op_sel_hi:[1,0]
	v_pk_mul_f32 v[12:13], v[12:13], v[86:87] op_sel_hi:[1,0]
	v_pk_mul_f32 v[10:11], v[10:11], v[86:87] op_sel_hi:[1,0]
	v_pk_mul_f32 v[8:9], v[8:9], v[86:87] op_sel_hi:[1,0]
	v_pk_mul_f32 v[6:7], v[6:7], v[86:87] op_sel_hi:[1,0]
	v_pk_mul_f32 v[4:5], v[4:5], v[86:87] op_sel_hi:[1,0]
	v_pk_mul_f32 v[2:3], v[2:3], v[86:87] op_sel_hi:[1,0]
	v_pk_mul_f32 v[0:1], v[0:1], v[86:87] op_sel_hi:[1,0]
